# GEMM epilogue stores marked non-temporal (nt) to keep A/B panels in L2; on top of early write-back v081
# baseline (speedup 1.0000x reference)
; #define LDA(dst, b, h) for (int m = 0; m < 4; ++m) for (int k = 0; k < 2; ++k) \
;     dst[m][k] = *reinterpret_cast<const bf16x8*>(SA(b, h) + lds_byte(wr * 64 + m * 16 + fr, k * 32 + fq * 8))
; #define LDB(dst, b, h) for (int n = 0; n < 2; ++n) for (int k = 0; k < 2; ++k) \
;     dst[n][k] = *reinterpret_cast<const bf16x8*>(SB(b, h) + lds_byte(wc * 32 + n * 16 + fr, k * 32 + fq * 8))
; #define MMA(ai, bj, At_, Bt_) do { __builtin_amdgcn_s_setprio(1); \
;     for (int m = 0; m < 4; ++m) for (int n = 0; n < 2; ++n) for (int k = 0; k < 2; ++k) \
;       acc[ai][bj][m][n] = __builtin_amdgcn_mfma_f32_16x16x32_bf16(Bt_[n][k], At_[m][k], acc[ai][bj][m][n], 0, 0, 0); \
;     __builtin_amdgcn_s_setprio(0); } while (0)
; #define WAIT_V(n) asm volatile("s_waitcnt vmcnt(" #n ")" ::: "memory")
; #define WAIT_L(n) asm volatile("s_waitcnt lgkmcnt(" #n ")" ::: "memory")
; #define BAR __builtin_amdgcn_s_barrier()
; #define SCHED __builtin_amdgcn_sched_barrier(0)
; #define STG(P, PTR, LD, O0) do { const bf16_t* _g = (PTR); \
;     __builtin_amdgcn_global_load_lds((const unsigned*)(_g + O0), (lds_u32*)((P) + swave * 1024), 16, 0, 0); \
;     __builtin_amdgcn_global_load_lds((const unsigned*)(_g + (size_t)64 * (LD) + O0), (lds_u32*)((P) + swave * 1024 + 8192), 16, 0, 0); } while (0)
; #define LDA(dst, b, h) for (int m = 0; m < 4; ++m) for (int k = 0; k < 2; ++k) \
;     dst[m][k] = *reinterpret_cast<const bf16x8*>(SA(b, h) + lds_byte(wr * 64 + m * 16 + fr, k * 32 + fq * 8))
; #define WAIT_V(n) asm volatile("s_waitcnt vmcnt(" #n ")" ::: "memory")
; __device__ __forceinline__ void gemm_stream(int swave, const GemmJob& J, char* shm, int vb, int G) {
;     ...
;     for (int t = 0; t < nt; t += 2) {
;       const bool last = (t == nt - 2);
;       const bf16_t* xA = last ? nA : cA; const bf16_t* xA1 = last ? nA1 : cA1; const int k2 = last ? 0 : t + 2;
;       const bf16_t* b2 = last ? nB : cB + (size_t)(t + 2) * 64; const bf16_t* b3 = b2 + 64;
;       LDB(B0, 0, 0); SCHED; LDA(At, 0, 0); STGA(SA(1, 1), cA, cA1, t + 1, 1);
;       WAIT_L(8); BAR; WAIT_L(0); MMA(0, 0, At, B0); BAR; SCHED;
;       LDB(B1, 0, 1); STG(SB(0, 0), b2, ldb, offB0);
;       BAR; WAIT_L(0); MMA(0, 1, At, B1); BAR;
;       LDA(At, 0, 1); STGA(SA(0, 0), xA, xA1, k2, 0);
;       BAR; WAIT_L(0); MMA(1, 0, At, B0); BAR; SCHED;
;       STG(SB(0, 1), b2 + hB, ldb, offB0);
;       WAIT_V(6); BAR; MMA(1, 1, At, B1); BAR;
.LBB0_729:
	ds_read_b128 v[164:167], v139
	ds_read_b128 v[168:171], v139 offset:1024
	ds_read_b128 v[172:175], v139 offset:2048
	ds_read_b128 v[176:179], v139 offset:3072
	s_cmp_eq_u32 s49, s29
	s_cselect_b64 s[68:69], -1, 0
	s_and_b64 s[64:65], s[68:69], exec
	s_cselect_b32 s52, s10, s8
	s_cselect_b32 s64, s11, s9
	s_add_i32 s33, s2, 2
	s_and_b64 s[68:69], s[68:69], exec
	s_cselect_b32 s71, s15, s21
	s_cselect_b32 s70, s14, s20
	s_cselect_b32 s68, 0, s33
	s_cselect_b32 s65, s12, s16
	s_cselect_b32 s66, s13, s17
	s_or_b32 s2, s2, 1
	s_cmp_lt_u32 s2, s36
	s_cselect_b64 vcc, -1, 0
	s_and_b64 s[2:3], vcc, exec
	s_cselect_b32 s3, 0, s36
	s_cselect_b32 s2, s38, s37
	s_not_b32 s3, s3
	s_add_i32 s94, s3, s29
	s_and_b64 s[72:73], vcc, exec
	s_cselect_b32 s3, s9, s17
	s_cselect_b32 s69, s8, s16
	s_lshl_b64 s[72:73], s[94:95], 7
	s_add_u32 s69, s69, s72
	s_addc_u32 s74, s3, s73
	s_mov_b32 s3, s95
	s_lshl_b64 s[72:73], s[2:3], 8
	s_add_u32 s72, s69, s72
	v_cndmask_b32_e32 v2, v138, v0, vcc
	s_addc_u32 s73, s74, s73
	s_add_i32 m0, s42, 0xc000
	s_lshl_b64 s[2:3], s[2:3], 7
	v_lshlrev_b64 v[212:213], 1, v[2:3]
	s_add_u32 s2, s72, s2
	v_lshl_add_u64 v[214:215], s[72:73], 0, v[212:213]
	s_addc_u32 s3, s73, s3
	ds_read_b128 v[180:183], v144
	ds_read_b128 v[188:191], v145
	ds_read_b128 v[196:199], v159
	ds_read_b128 v[204:207], v160
	global_load_lds_dwordx4 v[214:215], off
	v_lshl_add_u64 v[212:213], s[2:3], 0, v[212:213]
	s_add_i32 m0, s42, 0xe000
	s_nop 0
	global_load_lds_dwordx4 v[212:213], off
	s_waitcnt lgkmcnt(4)
	s_barrier
	s_waitcnt lgkmcnt(0)
	v_mfma_f32_16x16x32_bf16 v[128:131], v[164:167], v[180:183], v[128:131]
	ds_read_b128 v[184:187], v144 offset:1024
	v_mfma_f32_16x16x32_bf16 v[124:127], v[172:175], v[180:183], v[124:127]
	ds_read_b128 v[192:195], v145 offset:1024
	v_mfma_f32_16x16x32_bf16 v[120:123], v[164:167], v[188:191], v[120:123]
	ds_read_b128 v[200:203], v159 offset:1024
	v_mfma_f32_16x16x32_bf16 v[116:119], v[172:175], v[188:191], v[116:119]
	ds_read_b128 v[208:211], v160 offset:1024
	v_mfma_f32_16x16x32_bf16 v[104:107], v[164:167], v[196:199], v[104:107]
	v_mfma_f32_16x16x32_bf16 v[100:103], v[172:175], v[196:199], v[100:103]
	v_mfma_f32_16x16x32_bf16 v[88:91], v[164:167], v[204:207], v[88:91]
	v_mfma_f32_16x16x32_bf16 v[84:87], v[172:175], v[204:207], v[84:87]
	s_waitcnt lgkmcnt(0)
	v_mfma_f32_16x16x32_bf16 v[128:131], v[168:171], v[184:187], v[128:131]
	v_mfma_f32_16x16x32_bf16 v[124:127], v[176:179], v[184:187], v[124:127]
	v_mfma_f32_16x16x32_bf16 v[120:123], v[168:171], v[192:195], v[120:123]
	v_mfma_f32_16x16x32_bf16 v[116:119], v[176:179], v[192:195], v[116:119]
	v_mfma_f32_16x16x32_bf16 v[104:107], v[168:171], v[200:203], v[104:107]
	v_mfma_f32_16x16x32_bf16 v[100:103], v[176:179], v[200:203], v[100:103]
	v_mfma_f32_16x16x32_bf16 v[88:91], v[168:171], v[208:211], v[88:91]
	v_mfma_f32_16x16x32_bf16 v[84:87], v[176:179], v[208:211], v[84:87]
	s_barrier
	s_add_u32 s2, s70, s0
	s_mov_b32 m0, s43
	v_lshl_add_u64 v[228:229], s[70:71], 0, v[136:137]
	s_addc_u32 s3, s71, s1
	ds_read_b128 v[212:215], v161
	ds_read_b128 v[216:219], v161 offset:1024
	ds_read_b128 v[220:223], v161 offset:2048
	ds_read_b128 v[224:227], v161 offset:3072
	global_load_lds_dwordx4 v[228:229], off
	v_lshl_add_u64 v[230:231], s[2:3], 0, v[136:137]
	s_mov_b32 m0, s44
	s_nop 0
	global_load_lds_dwordx4 v[230:231], off
	s_barrier
	s_waitcnt lgkmcnt(0)
	v_mfma_f32_16x16x32_bf16 v[112:115], v[212:215], v[180:183], v[112:115]
	v_mfma_f32_16x16x32_bf16 v[108:111], v[220:223], v[180:183], v[108:111]
	s_cmp_lt_u32 s68, s36
	s_cselect_b64 vcc, -1, 0
	v_mfma_f32_16x16x32_bf16 v[96:99], v[212:215], v[188:191], v[96:99]
	s_and_b64 s[70:71], vcc, exec
	s_cselect_b32 s70, s38, s37
	v_mfma_f32_16x16x32_bf16 v[92:95], v[220:223], v[188:191], v[92:95]
	s_sub_i32 s69, s68, s36
	s_min_u32 s94, s68, s69
	v_mfma_f32_16x16x32_bf16 v[80:83], v[212:215], v[196:199], v[80:83]
	s_and_b64 s[72:73], vcc, exec
	s_cselect_b32 s69, s64, s66
	v_mfma_f32_16x16x32_bf16 v[76:79], v[220:223], v[196:199], v[76:79]
	s_cselect_b32 s71, s52, s65
	s_lshl_b64 s[72:73], s[94:95], 7
	v_mfma_f32_16x16x32_bf16 v[72:75], v[212:215], v[204:207], v[72:75]
	v_cndmask_b32_e32 v2, v138, v0, vcc
	s_add_u32 s72, s71, s72
	v_mfma_f32_16x16x32_bf16 v[68:71], v[220:223], v[204:207], v[68:71]
	s_mov_b32 s71, s95
	v_mfma_f32_16x16x32_bf16 v[112:115], v[216:219], v[184:187], v[112:115]
	s_addc_u32 s73, s69, s73
	v_mfma_f32_16x16x32_bf16 v[108:111], v[224:227], v[184:187], v[108:111]
	v_lshlrev_b64 v[232:233], 1, v[2:3]
	v_mfma_f32_16x16x32_bf16 v[96:99], v[216:219], v[192:195], v[96:99]
	s_lshl_b64 s[70:71], s[70:71], 7
	v_mfma_f32_16x16x32_bf16 v[92:95], v[224:227], v[192:195], v[92:95]
	v_lshl_add_u64 v[234:235], s[72:73], 0, v[232:233]
	v_mfma_f32_16x16x32_bf16 v[80:83], v[216:219], v[200:203], v[80:83]
	s_add_u32 s72, s72, s70
	v_mfma_f32_16x16x32_bf16 v[76:79], v[224:227], v[200:203], v[76:79]
	s_mov_b32 m0, s42
	v_mfma_f32_16x16x32_bf16 v[72:75], v[216:219], v[208:211], v[72:75]
	s_addc_u32 s73, s73, s71
	v_mfma_f32_16x16x32_bf16 v[68:71], v[224:227], v[208:211], v[68:71]
	s_barrier
	ds_read_b128 v[180:183], v144 offset:16384
	ds_read_b128 v[188:191], v145 offset:16384
	ds_read_b128 v[196:199], v159 offset:16384
	ds_read_b128 v[204:207], v160 offset:16384
	global_load_lds_dwordx4 v[234:235], off
	v_lshl_add_u64 v[234:235], s[72:73], 0, v[232:233]
	s_mov_b32 m0, s39
	s_nop 0
	global_load_lds_dwordx4 v[234:235], off
	s_barrier
; #define LDA(dst, b, h) for (int m = 0; m < 4; ++m) for (int k = 0; k < 2; ++k) \
;     dst[m][k] = *reinterpret_cast<const bf16x8*>(SA(b, h) + lds_byte(wr * 64 + m * 16 + fr, k * 32 + fq * 8))
; #define LDB(dst, b, h) for (int n = 0; n < 2; ++n) for (int k = 0; k < 2; ++k) \
;     dst[n][k] = *reinterpret_cast<const bf16x8*>(SB(b, h) + lds_byte(wc * 32 + n * 16 + fr, k * 32 + fq * 8))
; #define MMA(ai, bj, At_, Bt_) do { __builtin_amdgcn_s_setprio(1); \
;     for (int m = 0; m < 4; ++m) for (int n = 0; n < 2; ++n) for (int k = 0; k < 2; ++k) \
;       acc[ai][bj][m][n] = __builtin_amdgcn_mfma_f32_16x16x32_bf16(Bt_[n][k], At_[m][k], acc[ai][bj][m][n], 0, 0, 0); \
;     __builtin_amdgcn_s_setprio(0); } while (0)
; #define WAIT_V(n) asm volatile("s_waitcnt vmcnt(" #n ")" ::: "memory")
; #define WAIT_L(n) asm volatile("s_waitcnt lgkmcnt(" #n ")" ::: "memory")
; #define BAR __builtin_amdgcn_s_barrier()
; #define SCHED __builtin_amdgcn_sched_barrier(0)
; #define STG(P, PTR, LD, O0) do { const bf16_t* _g = (PTR); \
;     __builtin_amdgcn_global_load_lds((const unsigned*)(_g + O0), (lds_u32*)((P) + swave * 1024), 16, 0, 0); \
;     __builtin_amdgcn_global_load_lds((const unsigned*)(_g + (size_t)64 * (LD) + O0), (lds_u32*)((P) + swave * 1024 + 8192), 16, 0, 0); } while (0)
; #define LDA(dst, b, h) for (int m = 0; m < 4; ++m) for (int k = 0; k < 2; ++k) \
;     dst[m][k] = *reinterpret_cast<const bf16x8*>(SA(b, h) + lds_byte(wr * 64 + m * 16 + fr, k * 32 + fq * 8))
; #define LDB(dst, b, h) for (int n = 0; n < 2; ++n) for (int k = 0; k < 2; ++k) \
;     dst[n][k] = *reinterpret_cast<const bf16x8*>(SB(b, h) + lds_byte(wc * 32 + n * 16 + fr, k * 32 + fq * 8))
; #define WAIT_V(n) asm volatile("s_waitcnt vmcnt(" #n ")" ::: "memory")
; __device__ __forceinline__ void gemm_stream(int swave, const GemmJob& J, char* shm, int vb, int G) {
;     ...
;       LDA(At, 0, 1); STGA(SA(0, 0), xA, xA1, k2, 0);
;       BAR; WAIT_L(0); MMA(1, 0, At, B0); BAR; SCHED;
;       STG(SB(0, 1), b2 + hB, ldb, offB0);
;       WAIT_V(6); BAR; MMA(1, 1, At, B1); BAR;
;       LDB(B0, 1, 0); SCHED; LDA(At, 1, 0); STGA(SA(0, 1), xA, xA1, k2, 1);
;       WAIT_L(8); BAR; WAIT_L(0); MMA(0, 0, At, B0); BAR; SCHED;
;       LDB(B1, 1, 1); STG(SB(1, 0), b3, ldb, offB0);
;       BAR; WAIT_L(0); MMA(0, 1, At, B1); BAR;
;       LDA(At, 1, 1); STGA(SA(1, 0), xA, xA1, k2 + 1, 0);
	s_waitcnt lgkmcnt(0)
	v_mfma_f32_16x16x32_bf16 v[64:67], v[164:167], v[180:183], v[64:67]
	ds_read_b128 v[184:187], v144 offset:17408
	v_mfma_f32_16x16x32_bf16 v[60:63], v[172:175], v[180:183], v[60:63]
	ds_read_b128 v[192:195], v145 offset:17408
	v_mfma_f32_16x16x32_bf16 v[56:59], v[164:167], v[188:191], v[56:59]
	ds_read_b128 v[200:203], v159 offset:17408
	v_mfma_f32_16x16x32_bf16 v[52:55], v[172:175], v[188:191], v[52:55]
	ds_read_b128 v[208:211], v160 offset:17408
	v_mfma_f32_16x16x32_bf16 v[40:43], v[164:167], v[196:199], v[40:43]
	v_mfma_f32_16x16x32_bf16 v[36:39], v[172:175], v[196:199], v[36:39]
	v_mfma_f32_16x16x32_bf16 v[24:27], v[164:167], v[204:207], v[24:27]
	v_mfma_f32_16x16x32_bf16 v[20:23], v[172:175], v[204:207], v[20:23]
	s_waitcnt lgkmcnt(0)
	v_mfma_f32_16x16x32_bf16 v[64:67], v[168:171], v[184:187], v[64:67]
	v_mfma_f32_16x16x32_bf16 v[60:63], v[176:179], v[184:187], v[60:63]
	v_mfma_f32_16x16x32_bf16 v[56:59], v[168:171], v[192:195], v[56:59]
	v_mfma_f32_16x16x32_bf16 v[52:55], v[176:179], v[192:195], v[52:55]
	v_mfma_f32_16x16x32_bf16 v[40:43], v[168:171], v[200:203], v[40:43]
	v_mfma_f32_16x16x32_bf16 v[36:39], v[176:179], v[200:203], v[36:39]
	v_mfma_f32_16x16x32_bf16 v[24:27], v[168:171], v[208:211], v[24:27]
	v_mfma_f32_16x16x32_bf16 v[20:23], v[176:179], v[208:211], v[20:23]
	s_barrier
	s_add_u32 s2, s2, s0
	s_addc_u32 s3, s3, s1
	v_lshl_add_u64 v[234:235], s[2:3], 0, v[136:137]
	s_add_u32 s2, s2, s0
	s_mov_b32 m0, s45
	s_addc_u32 s3, s3, s1
	global_load_lds_dwordx4 v[234:235], off
	v_lshl_add_u64 v[236:237], s[2:3], 0, v[136:137]
	s_mov_b32 m0, s46
	s_nop 0
	global_load_lds_dwordx4 v[236:237], off
	s_waitcnt vmcnt(6)
	s_barrier
	v_mfma_f32_16x16x32_bf16 v[48:51], v[212:215], v[180:183], v[48:51]
	v_mfma_f32_16x16x32_bf16 v[44:47], v[220:223], v[180:183], v[44:47]
	v_mfma_f32_16x16x32_bf16 v[32:35], v[212:215], v[188:191], v[32:35]
	v_mfma_f32_16x16x32_bf16 v[28:31], v[220:223], v[188:191], v[28:31]
	v_mfma_f32_16x16x32_bf16 v[16:19], v[212:215], v[196:199], v[16:19]
	v_mfma_f32_16x16x32_bf16 v[12:15], v[220:223], v[196:199], v[12:15]
	v_mfma_f32_16x16x32_bf16 v[8:11], v[212:215], v[204:207], v[8:11]
	v_mfma_f32_16x16x32_bf16 v[4:7], v[220:223], v[204:207], v[4:7]
	v_mfma_f32_16x16x32_bf16 v[48:51], v[216:219], v[184:187], v[48:51]
	v_mfma_f32_16x16x32_bf16 v[44:47], v[224:227], v[184:187], v[44:47]
	v_mfma_f32_16x16x32_bf16 v[32:35], v[216:219], v[192:195], v[32:35]
	v_mfma_f32_16x16x32_bf16 v[28:31], v[224:227], v[192:195], v[28:31]
	v_mfma_f32_16x16x32_bf16 v[16:19], v[216:219], v[200:203], v[16:19]
	v_mfma_f32_16x16x32_bf16 v[12:15], v[224:227], v[200:203], v[12:15]
	v_mfma_f32_16x16x32_bf16 v[8:11], v[216:219], v[208:211], v[8:11]
	v_mfma_f32_16x16x32_bf16 v[4:7], v[224:227], v[208:211], v[4:7]
	s_barrier
	ds_read_b128 v[164:167], v162
	ds_read_b128 v[168:171], v162 offset:1024
	ds_read_b128 v[172:175], v162 offset:2048
	ds_read_b128 v[176:179], v162 offset:3072
	s_add_u32 s2, s72, s70
	s_addc_u32 s3, s73, s71
	v_lshl_add_u64 v[212:213], s[2:3], 0, v[232:233]
	s_add_u32 s2, s2, s70
	s_mov_b32 m0, s47
	s_addc_u32 s3, s3, s71
	ds_read_b128 v[180:183], v144 offset:32768
	ds_read_b128 v[188:191], v145 offset:32768
	ds_read_b128 v[196:199], v159 offset:32768
	ds_read_b128 v[204:207], v160 offset:32768
	global_load_lds_dwordx4 v[212:213], off
	v_lshl_add_u64 v[212:213], s[2:3], 0, v[232:233]
	s_mov_b32 m0, s48
	s_nop 0
	global_load_lds_dwordx4 v[212:213], off
	s_waitcnt lgkmcnt(4)
	s_barrier
	s_waitcnt lgkmcnt(0)
	v_mfma_f32_16x16x32_bf16 v[128:131], v[164:167], v[180:183], v[128:131]
	ds_read_b128 v[184:187], v144 offset:33792
	v_mfma_f32_16x16x32_bf16 v[124:127], v[172:175], v[180:183], v[124:127]
	ds_read_b128 v[192:195], v145 offset:33792
	v_mfma_f32_16x16x32_bf16 v[120:123], v[164:167], v[188:191], v[120:123]
	ds_read_b128 v[200:203], v159 offset:33792
	v_mfma_f32_16x16x32_bf16 v[116:119], v[172:175], v[188:191], v[116:119]
	ds_read_b128 v[208:211], v160 offset:33792
	v_mfma_f32_16x16x32_bf16 v[104:107], v[164:167], v[196:199], v[104:107]
	v_mfma_f32_16x16x32_bf16 v[100:103], v[172:175], v[196:199], v[100:103]
	v_mfma_f32_16x16x32_bf16 v[88:91], v[164:167], v[204:207], v[88:91]
	v_mfma_f32_16x16x32_bf16 v[84:87], v[172:175], v[204:207], v[84:87]
	s_waitcnt lgkmcnt(0)
	v_mfma_f32_16x16x32_bf16 v[128:131], v[168:171], v[184:187], v[128:131]
	v_mfma_f32_16x16x32_bf16 v[124:127], v[176:179], v[184:187], v[124:127]
	v_mfma_f32_16x16x32_bf16 v[120:123], v[168:171], v[192:195], v[120:123]
	v_mfma_f32_16x16x32_bf16 v[116:119], v[176:179], v[192:195], v[116:119]
	v_mfma_f32_16x16x32_bf16 v[104:107], v[168:171], v[200:203], v[104:107]
	v_mfma_f32_16x16x32_bf16 v[100:103], v[176:179], v[200:203], v[100:103]
	v_mfma_f32_16x16x32_bf16 v[88:91], v[168:171], v[208:211], v[88:91]
	v_mfma_f32_16x16x32_bf16 v[84:87], v[176:179], v[208:211], v[84:87]
	s_barrier
	v_lshl_add_u64 v[228:229], v[228:229], 0, s[22:23]
	s_add_i32 m0, s42, 0x18000
	ds_read_b128 v[212:215], v163
	ds_read_b128 v[216:219], v163 offset:1024
	ds_read_b128 v[220:223], v163 offset:2048
	ds_read_b128 v[224:227], v163 offset:3072
	global_load_lds_dwordx4 v[228:229], off
	v_lshl_add_u64 v[228:229], v[230:231], 0, s[22:23]
	s_add_i32 m0, s42, 0x1a000
	s_nop 0
	global_load_lds_dwordx4 v[228:229], off
	s_barrier
; #define LDA(dst, b, h) for (int m = 0; m < 4; ++m) for (int k = 0; k < 2; ++k) \
;     dst[m][k] = *reinterpret_cast<const bf16x8*>(SA(b, h) + lds_byte(wr * 64 + m * 16 + fr, k * 32 + fq * 8))
; #define MMA(ai, bj, At_, Bt_) do { __builtin_amdgcn_s_setprio(1); \
;     for (int m = 0; m < 4; ++m) for (int n = 0; n < 2; ++n) for (int k = 0; k < 2; ++k) \
;       acc[ai][bj][m][n] = __builtin_amdgcn_mfma_f32_16x16x32_bf16(Bt_[n][k], At_[m][k], acc[ai][bj][m][n], 0, 0, 0); \
;     __builtin_amdgcn_s_setprio(0); } while (0)
; #define WAIT_V(n) asm volatile("s_waitcnt vmcnt(" #n ")" ::: "memory")
; #define WAIT_L(n) asm volatile("s_waitcnt lgkmcnt(" #n ")" ::: "memory")
; #define BAR __builtin_amdgcn_s_barrier()
; #define SCHED __builtin_amdgcn_sched_barrier(0)
; #define STG(P, PTR, LD, O0) do { const bf16_t* _g = (PTR); \
;     __builtin_amdgcn_global_load_lds((const unsigned*)(_g + O0), (lds_u32*)((P) + swave * 1024), 16, 0, 0); \
;     __builtin_amdgcn_global_load_lds((const unsigned*)(_g + (size_t)64 * (LD) + O0), (lds_u32*)((P) + swave * 1024 + 8192), 16, 0, 0); } while (0)
; #define LDA(dst, b, h) for (int m = 0; m < 4; ++m) for (int k = 0; k < 2; ++k) \
;     dst[m][k] = *reinterpret_cast<const bf16x8*>(SA(b, h) + lds_byte(wr * 64 + m * 16 + fr, k * 32 + fq * 8))
; #define MMA(ai, bj, At_, Bt_) do { __builtin_amdgcn_s_setprio(1); \
;     for (int m = 0; m < 4; ++m) for (int n = 0; n < 2; ++n) for (int k = 0; k < 2; ++k) \
;       acc[ai][bj][m][n] = __builtin_amdgcn_mfma_f32_16x16x32_bf16(Bt_[n][k], At_[m][k], acc[ai][bj][m][n], 0, 0, 0); \
;     __builtin_amdgcn_s_setprio(0); } while (0)
; #define WAIT_V(n) asm volatile("s_waitcnt vmcnt(" #n ")" ::: "memory")
; #define WAIT_L(n) asm volatile("s_waitcnt lgkmcnt(" #n ")" ::: "memory")
; #define BAR __builtin_amdgcn_s_barrier()
; #define SCHED __builtin_amdgcn_sched_barrier(0)
; __device__ __forceinline__ void gemm_stream(int swave, const GemmJob& J, char* shm, int vb, int G) {
;     ...
;       BAR; WAIT_L(0); MMA(0, 1, At, B1); BAR;
;       LDA(At, 1, 1); STGA(SA(1, 0), xA, xA1, k2 + 1, 0);
;       BAR; WAIT_L(0); MMA(1, 0, At, B0); BAR; SCHED;
;       STG(SB(1, 1), b3 + hB, ldb, offB0);
;       WAIT_V(6); BAR; MMA(1, 1, At, B1); BAR;
;     }
	s_waitcnt lgkmcnt(0)
	v_mfma_f32_16x16x32_bf16 v[112:115], v[212:215], v[180:183], v[112:115]
	v_mfma_f32_16x16x32_bf16 v[108:111], v[220:223], v[180:183], v[108:111]
	s_or_b32 s68, s68, 1
	s_cmp_lt_u32 s68, s36
	v_mfma_f32_16x16x32_bf16 v[96:99], v[212:215], v[188:191], v[96:99]
	s_cselect_b64 vcc, -1, 0
	s_and_b64 s[2:3], vcc, exec
	v_mfma_f32_16x16x32_bf16 v[92:95], v[220:223], v[188:191], v[92:95]
	s_cselect_b32 s69, s38, s37
	s_sub_i32 s2, s68, s36
	v_mfma_f32_16x16x32_bf16 v[80:83], v[212:215], v[196:199], v[80:83]
	s_min_u32 s94, s68, s2
	s_and_b64 s[2:3], vcc, exec
	v_mfma_f32_16x16x32_bf16 v[76:79], v[220:223], v[196:199], v[76:79]
	s_cselect_b32 s64, s64, s66
	s_cselect_b32 s52, s52, s65
	v_mfma_f32_16x16x32_bf16 v[72:75], v[212:215], v[204:207], v[72:75]
	s_lshl_b64 s[2:3], s[94:95], 7
	v_cndmask_b32_e32 v2, v138, v0, vcc
	v_mfma_f32_16x16x32_bf16 v[68:71], v[220:223], v[204:207], v[68:71]
	s_add_u32 s2, s52, s2
	v_mfma_f32_16x16x32_bf16 v[112:115], v[216:219], v[184:187], v[112:115]
	s_addc_u32 s3, s64, s3
	v_mfma_f32_16x16x32_bf16 v[108:111], v[224:227], v[184:187], v[108:111]
	v_lshlrev_b64 v[228:229], 1, v[2:3]
	v_mfma_f32_16x16x32_bf16 v[96:99], v[216:219], v[192:195], v[96:99]
	s_lshl_b32 s52, s69, 7
	v_mfma_f32_16x16x32_bf16 v[92:95], v[224:227], v[192:195], v[92:95]
	v_lshl_add_u64 v[230:231], s[2:3], 0, v[228:229]
	v_mfma_f32_16x16x32_bf16 v[80:83], v[216:219], v[200:203], v[80:83]
	s_add_u32 s2, s2, s52
	v_mfma_f32_16x16x32_bf16 v[76:79], v[224:227], v[200:203], v[76:79]
	s_mov_b32 m0, s54
	v_mfma_f32_16x16x32_bf16 v[72:75], v[216:219], v[208:211], v[72:75]
	s_addc_u32 s3, s3, 0
	v_mfma_f32_16x16x32_bf16 v[68:71], v[224:227], v[208:211], v[68:71]
	s_barrier
	ds_read_b128 v[180:183], v144 offset:49152
	ds_read_b128 v[188:191], v145 offset:49152
	ds_read_b128 v[196:199], v159 offset:49152
	ds_read_b128 v[204:207], v160 offset:49152
	global_load_lds_dwordx4 v[230:231], off
	v_lshl_add_u64 v[228:229], s[2:3], 0, v[228:229]
	s_mov_b32 m0, s55
	s_nop 0
	global_load_lds_dwordx4 v[228:229], off
	s_barrier
	s_waitcnt lgkmcnt(0)
	v_mfma_f32_16x16x32_bf16 v[64:67], v[164:167], v[180:183], v[64:67]
	ds_read_b128 v[184:187], v144 offset:50176
	v_mfma_f32_16x16x32_bf16 v[60:63], v[172:175], v[180:183], v[60:63]
	ds_read_b128 v[192:195], v145 offset:50176
	v_mfma_f32_16x16x32_bf16 v[56:59], v[164:167], v[188:191], v[56:59]
	ds_read_b128 v[200:203], v159 offset:50176
	v_mfma_f32_16x16x32_bf16 v[52:55], v[172:175], v[188:191], v[52:55]
	ds_read_b128 v[208:211], v160 offset:50176
	v_mfma_f32_16x16x32_bf16 v[40:43], v[164:167], v[196:199], v[40:43]
	v_mfma_f32_16x16x32_bf16 v[36:39], v[172:175], v[196:199], v[36:39]
	v_mfma_f32_16x16x32_bf16 v[24:27], v[164:167], v[204:207], v[24:27]
	v_mfma_f32_16x16x32_bf16 v[20:23], v[172:175], v[204:207], v[20:23]
	s_waitcnt lgkmcnt(0)
	v_mfma_f32_16x16x32_bf16 v[64:67], v[168:171], v[184:187], v[64:67]
	v_mfma_f32_16x16x32_bf16 v[60:63], v[176:179], v[184:187], v[60:63]
	v_mfma_f32_16x16x32_bf16 v[56:59], v[168:171], v[192:195], v[56:59]
	v_mfma_f32_16x16x32_bf16 v[52:55], v[176:179], v[192:195], v[52:55]
	v_mfma_f32_16x16x32_bf16 v[40:43], v[168:171], v[200:203], v[40:43]
	v_mfma_f32_16x16x32_bf16 v[36:39], v[176:179], v[200:203], v[36:39]
	v_mfma_f32_16x16x32_bf16 v[24:27], v[168:171], v[208:211], v[24:27]
	v_mfma_f32_16x16x32_bf16 v[20:23], v[176:179], v[208:211], v[20:23]
	s_barrier
	v_lshl_add_u64 v[164:165], v[234:235], 0, s[22:23]
	s_add_i32 m0, s42, 0x1c000
	s_nop 0
	global_load_lds_dwordx4 v[164:165], off
	v_lshl_add_u64 v[164:165], v[236:237], 0, s[22:23]
	s_add_i32 m0, s42, 0x1e000
	s_nop 0
	global_load_lds_dwordx4 v[164:165], off
	s_waitcnt vmcnt(6)
	s_barrier
	v_mfma_f32_16x16x32_bf16 v[48:51], v[212:215], v[180:183], v[48:51]
	v_mfma_f32_16x16x32_bf16 v[44:47], v[220:223], v[180:183], v[44:47]
	s_add_i32 s29, s29, 2
	v_mfma_f32_16x16x32_bf16 v[32:35], v[212:215], v[188:191], v[32:35]
	s_add_u32 s20, s20, 0x100
	v_mfma_f32_16x16x32_bf16 v[28:31], v[220:223], v[188:191], v[28:31]
	s_addc_u32 s21, s21, 0
	v_mfma_f32_16x16x32_bf16 v[16:19], v[212:215], v[196:199], v[16:19]
	s_cmp_ge_u32 s33, s49
	v_mfma_f32_16x16x32_bf16 v[12:15], v[220:223], v[196:199], v[12:15]
	s_mov_b32 s2, s33
	v_mfma_f32_16x16x32_bf16 v[8:11], v[212:215], v[204:207], v[8:11]
	v_mfma_f32_16x16x32_bf16 v[4:7], v[220:223], v[204:207], v[4:7]
	v_mfma_f32_16x16x32_bf16 v[48:51], v[216:219], v[184:187], v[48:51]
	v_mfma_f32_16x16x32_bf16 v[44:47], v[224:227], v[184:187], v[44:47]
	v_mfma_f32_16x16x32_bf16 v[32:35], v[216:219], v[192:195], v[32:35]
	v_mfma_f32_16x16x32_bf16 v[28:31], v[224:227], v[192:195], v[28:31]
	v_mfma_f32_16x16x32_bf16 v[16:19], v[216:219], v[200:203], v[16:19]
	v_mfma_f32_16x16x32_bf16 v[12:15], v[224:227], v[200:203], v[12:15]
	v_mfma_f32_16x16x32_bf16 v[8:11], v[216:219], v[208:211], v[8:11]
	v_mfma_f32_16x16x32_bf16 v[4:7], v[224:227], v[208:211], v[4:7]
	s_barrier
; __device__ __forceinline__ unsigned pk2(float lo, float hi) { f32x2_t v = {lo, hi}; bf16x2_t b = __builtin_convertvector(v, bf16x2_t); return __builtin_bit_cast(unsigned, b); }
; __device__ __forceinline__ void gemm_stream(int swave, const GemmJob& J, char* shm, int vb, int G) {
;     ...
;     {
;       bf16_t* C = (bf16_t*)((char*)J.c0 + (size_t)cg * J.strideC);
; #pragma unroll
;       for (int ai = 0; ai < 2; ++ai)
; #pragma unroll
;         for (int m = 0; m < 4; ++m)
; #pragma unroll
;           for (int bj = 0; bj < 2; ++bj) {
;             const f32x4 v0 = acc[ai][bj][m][0], v1 = acc[ai][bj][m][1];
;             uint4 o; o.x = pk2(v0[0], v0[1]); o.y = pk2(v0[2], v0[3]); o.z = pk2(v1[0], v1[1]); o.w = pk2(v1[2], v1[3]);
;             *(uint4*)(C + (size_t)(cbrow + ai * 128 + wr * 64 + m * 16 + fr) * J.ldc + cbcol + bj * 128 + wc * 32 + fq * 8) = o;
;           }
;     }
;     if (!has_next) break;
; #pragma unroll
;     for (int a_ = 0; a_ < 2; ++a_)
; #pragma unroll
;       for (int b_ = 0; b_ < 2; ++b_)
; #pragma unroll
;         for (int m = 0; m < 4; ++m)
; #pragma unroll
;           for (int n = 0; n < 2; ++n) acc[a_][b_][m][n] = (f32x4){0.f, 0.f, 0.f, 0.f};
;     id = nid; cg = ng; cbrow = nbrow; cbcol = nbcol; cA = nA; cA1 = nA1; cB = nB;
;   }
	s_cbranch_scc0 .LBB0_729
	v_add_u32_e32 v164, s5, v1
	s_ashr_i32 s5, s4, 31
	s_lshl_b64 s[2:3], s[4:5], 1
	v_ashrrev_i32_e32 v2, 31, v164
	s_add_u32 s2, s50, s2
	v_cvt_pk_bf16_f32 v128, v128, v129
	v_cvt_pk_bf16_f32 v129, v130, v131
	v_cvt_pk_bf16_f32 v130, v124, v125
	v_mul_lo_u32 v2, v2, s18
	v_mad_u64_u32 v[124:125], s[4:5], v164, s18, 0
	s_addc_u32 s3, s51, s3
	v_add_u32_e32 v125, v125, v2
	v_lshl_add_u64 v[124:125], v[124:125], 1, s[2:3]
	v_mov_b32_e32 v141, v3
	v_lshl_add_u64 v[124:125], v[124:125], 0, v[140:141]
	v_mov_b32_e32 v143, v3
	v_lshl_add_u64 v[124:125], v[124:125], 0, v[142:143]
	s_lshl_b32 s2, s18, 5
	s_mov_b32 s3, 0
	s_mul_i32 s4, s18, 0xa0
	s_mov_b32 s5, 0
	v_cvt_pk_bf16_f32 v112, v112, v113
	v_cvt_pk_bf16_f32 v113, v114, v115
	v_cvt_pk_bf16_f32 v114, v108, v109
	v_cvt_pk_bf16_f32 v115, v110, v111
	global_store_dwordx4 v[124:125], v[112:115], off offset:256 nt
	v_cvt_pk_bf16_f32 v131, v126, v127
	v_cvt_pk_bf16_f32 v96, v96, v97
	v_lshl_add_u64 v[112:113], v[124:125], 0, s[2:3]
	v_cvt_pk_bf16_f32 v97, v98, v99
	v_cvt_pk_bf16_f32 v98, v92, v93
	v_cvt_pk_bf16_f32 v99, v94, v95
	global_store_dwordx4 v[124:125], v[128:131], off nt
	global_store_dwordx4 v[112:113], v[96:99], off offset:256 nt
	v_cvt_pk_bf16_f32 v108, v120, v121
	v_cvt_pk_bf16_f32 v109, v122, v123
	v_lshl_add_u64 v[96:97], v[112:113], 0, s[2:3]
	v_cvt_pk_bf16_f32 v110, v116, v117
	v_cvt_pk_bf16_f32 v111, v118, v119
	v_cvt_pk_bf16_f32 v80, v80, v81
	v_cvt_pk_bf16_f32 v81, v82, v83
	v_cvt_pk_bf16_f32 v82, v76, v77
	v_cvt_pk_bf16_f32 v83, v78, v79
	global_store_dwordx4 v[112:113], v[108:111], off nt
	global_store_dwordx4 v[96:97], v[80:83], off offset:256 nt
	v_cvt_pk_bf16_f32 v64, v64, v65
	v_cvt_pk_bf16_f32 v65, v66, v67
	v_lshl_add_u64 v[80:81], v[96:97], 0, s[2:3]
	v_cvt_pk_bf16_f32 v66, v60, v61
	v_lshl_add_u64 v[60:61], v[80:81], 0, s[4:5]
	v_cvt_pk_bf16_f32 v72, v72, v73
	v_cvt_pk_bf16_f32 v73, v74, v75
	v_cvt_pk_bf16_f32 v74, v68, v69
	v_cvt_pk_bf16_f32 v67, v62, v63
	v_cvt_pk_bf16_f32 v92, v104, v105
	v_cvt_pk_bf16_f32 v93, v106, v107
	v_cvt_pk_bf16_f32 v94, v100, v101
	v_cvt_pk_bf16_f32 v95, v102, v103
	v_cvt_pk_bf16_f32 v76, v88, v89
	v_cvt_pk_bf16_f32 v77, v90, v91
	v_cvt_pk_bf16_f32 v78, v84, v85
	v_cvt_pk_bf16_f32 v79, v86, v87
	v_cvt_pk_bf16_f32 v75, v70, v71
	v_cvt_pk_bf16_f32 v48, v48, v49
	v_cvt_pk_bf16_f32 v49, v50, v51
	v_cvt_pk_bf16_f32 v50, v44, v45
	v_cvt_pk_bf16_f32 v51, v46, v47
	global_store_dwordx4 v[96:97], v[92:95], off nt
	global_store_dwordx4 v[80:81], v[76:79], off nt
	global_store_dwordx4 v[80:81], v[72:75], off offset:256 nt
	global_store_dwordx4 v[60:61], v[48:51], off offset:256 nt
	v_cvt_pk_bf16_f32 v32, v32, v33
	v_cvt_pk_bf16_f32 v33, v34, v35
	v_lshl_add_u64 v[48:49], v[60:61], 0, s[2:3]
	v_cvt_pk_bf16_f32 v34, v28, v29
	v_cvt_pk_bf16_f32 v35, v30, v31
	global_store_dwordx4 v[60:61], v[64:67], off nt
	global_store_dwordx4 v[48:49], v[32:35], off offset:256 nt
	v_cvt_pk_bf16_f32 v44, v56, v57
	v_cvt_pk_bf16_f32 v45, v58, v59
	v_lshl_add_u64 v[32:33], v[48:49], 0, s[2:3]
	v_cvt_pk_bf16_f32 v46, v52, v53
	v_cvt_pk_bf16_f32 v47, v54, v55
	v_cvt_pk_bf16_f32 v16, v16, v17
	v_cvt_pk_bf16_f32 v17, v18, v19
	v_cvt_pk_bf16_f32 v18, v12, v13
	v_cvt_pk_bf16_f32 v19, v14, v15
	global_store_dwordx4 v[48:49], v[44:47], off nt
	global_store_dwordx4 v[32:33], v[16:19], off offset:256 nt
	v_cvt_pk_bf16_f32 v28, v40, v41
	v_cvt_pk_bf16_f32 v29, v42, v43
	v_lshl_add_u64 v[16:17], v[32:33], 0, s[2:3]
	v_cvt_pk_bf16_f32 v30, v36, v37
	v_cvt_pk_bf16_f32 v31, v38, v39
	v_cvt_pk_bf16_f32 v12, v24, v25
	v_cvt_pk_bf16_f32 v13, v26, v27
	v_cvt_pk_bf16_f32 v14, v20, v21
	v_cvt_pk_bf16_f32 v15, v22, v23
	v_cvt_pk_bf16_f32 v8, v8, v9
	v_cvt_pk_bf16_f32 v9, v10, v11
	v_cvt_pk_bf16_f32 v10, v4, v5
	v_cvt_pk_bf16_f32 v11, v6, v7
	s_and_b64 vcc, exec, s[6:7]
	s_mov_b64 s[2:3], s[14:15]
	s_mov_b64 s[16:17], s[12:13]
	s_mov_b64 s[8:9], s[10:11]
	s_mov_b32 s4, s56
	s_mov_b32 s5, s28
	global_store_dwordx4 v[32:33], v[28:31], off nt
	global_store_dwordx4 v[16:17], v[12:15], off nt
	global_store_dwordx4 v[16:17], v[8:11], off offset:256 nt
	s_cbranch_vccz .LBB0_726
	s_waitcnt vmcnt(0)
	s_movk_i32 s66, 0x100
	v_cmp_gt_u32_e32 vcc, s66, v135
	s_and_saveexec_b64 s[0:1], vcc
	s_cbranch_execz .LBB0_733
	s_barrier
